# granule area cleared in phase 0 with system-scope stores (robustness)
# baseline (speedup 1.0000x reference)
; __global__ void __launch_bounds__(512, 2) hybrid_fwd(Params P) {
;     ...
;         float* scr = (float*)(lds + wave * 16384);
;         constexpr int I_IN = 16 * 48, I_OUT = 16 * 32, I_G = 16 * 88, I_DN = 44 * 32, I_GLU = 4 * 8, I_MOD = 16 * 192;
;         constexpr int I_LAYER = I_IN + I_OUT + 2 * I_G + I_DN + I_GLU + I_MOD;
;         for (int it = gw; it < DEPTH * I_LAYER; it += NGW) {
.LBB0_56:
	s_or_b64 exec, exec, s[10:11]
	s_lshl_b32 s0, s26, 3
	s_add_i32 s0, s0, s25
	s_lshl_b32 s0, s0, 8
	s_add_u32 s2, s6, 0x600000
	s_addc_u32 s3, s7, 0
	v_lshl_add_u32 v0, v24, 2, s0
	v_mov_b32_e32 v1, 0
	global_store_dword v0, v1, s[2:3] sc0 sc1
	s_lshl_b32 s0, s26, 3
	s_add_i32 s10, s0, s25
	s_cmp_gt_i32 s10, 0x867f
	s_cbranch_scc1 .LBB0_116
	s_lshl_b32 s0, s25, 14
	s_lshl_b32 s11, s24, 3
	s_add_i32 s0, s0, 0
	s_add_u32 s12, s6, 0xe100000
	s_addc_u32 s13, s7, 0
	s_add_u32 s14, s6, 0x1600000
	s_addc_u32 s15, s7, 0
	s_add_u32 s16, s6, 0x6800000
	s_addc_u32 s17, s7, 0
	v_ashrrev_i32_e32 v4, 5, v24
	s_movk_i32 s2, 0x84
	s_add_u32 s18, s6, 0x3c00000
	v_mul_lo_u32 v0, v4, s2
	v_lshlrev_b32_e32 v2, 2, v8
	s_addc_u32 s19, s7, 0
	v_add3_u32 v5, s0, v0, v2
	v_lshlrev_b32_e32 v0, 3, v24
	s_add_u32 s20, s6, 0x3400000
	v_ashrrev_i32_e32 v6, 3, v24
	v_and_b32_e32 v2, 56, v0
	s_addc_u32 s21, s7, 0
	v_mul_u32_u24_e32 v0, 0x84, v2
	v_lshlrev_b32_e32 v3, 2, v6
	s_add_u32 s22, s6, 0x2800000
	s_mov_b32 s1, 0
	v_mov_b32_e32 v1, 0
	v_add3_u32 v7, s0, v0, v3
	v_add_u32_e32 v10, 8, v6
	v_add_u32_e32 v11, 16, v6
	v_add_u32_e32 v12, 24, v6
	s_addc_u32 s23, s7, 0
	s_lshl_b32 s25, s10, 1
	s_lshl_b32 s26, s24, 4
	s_lshl_b32 s27, s10, 5
	s_lshl_b32 s28, s24, 8
	s_lshl_b32 s29, s10, 3
	s_lshl_b32 s30, s24, 6
	s_movk_i32 s31, 0x6000
	s_movk_i32 s33, 0x1000
	s_movk_i32 s34, 0x2000
	s_movk_i32 s35, 0x3000
	s_movk_i32 s36, 0x4000
	s_movk_i32 s37, 0x5000
	s_movk_i32 s38, 0x7000
	s_mov_b32 s39, 0x8000
	s_mov_b32 s40, 0x9000
	s_mov_b32 s41, 0xa000
	s_mov_b32 s42, 0xb000
	s_mov_b32 s43, 0xc000
	s_mov_b32 s44, 0xd000
	s_mov_b32 s45, 0xe000
	s_mov_b32 s46, 0xf000
	s_mov_b32 s47, 0x10000
	s_mov_b32 s48, 0x12000
	s_mov_b32 s49, 0x14000
	s_mov_b32 s50, 0x16000
	s_mov_b32 s51, 0x18000
	s_mov_b32 s52, 0x1a000
	s_mov_b32 s53, 0x1c000
	s_mov_b32 s54, 0x1e000
	s_mov_b32 s55, 0x20000
	s_mov_b32 s56, 0x22000
	s_mov_b32 s57, 0x24000
	s_mov_b32 s58, 0x26000
	s_mov_b32 s59, 0x28000
	s_mov_b32 s60, 0x2a000
	s_mov_b32 s61, 0x2c000
	s_mov_b32 s62, 0x2e000
	s_mov_b32 s63, 0x30000
	s_mov_b32 s64, 0x32000
	s_mov_b32 s65, 0x34000
	s_mov_b32 s66, 0x36000
	s_mov_b32 s67, 0x38000
	s_mov_b32 s68, 0x3a000
	s_mov_b32 s69, 0x3c000
	s_mov_b32 s70, 0x3e000
	s_movk_i32 s71, 0x1600
	s_movk_i32 s72, 0x2c00
	s_movk_i32 s73, 0x1800
	v_lshlrev_b32_e32 v0, 2, v8
	v_add_u32_e32 v8, 0x400, v5
	v_add_u32_e32 v13, 0x800, v5
	v_add_u32_e32 v14, 0xc00, v5
	v_add_u32_e32 v16, 0x1000, v5
	v_add_u32_e32 v17, 0x1400, v5
	v_add_u32_e32 v18, 0x1800, v5
	v_add_u32_e32 v19, 0x1c00, v5
	v_lshlrev_b32_e32 v2, 1, v2
	s_branch .LBB0_76
